# strategy 7.5: seven half-dead v_pk_add_f32 in the dilated-attention softmax replaced by scalar v_add_f32
# speedup vs baseline: 1.0068x; 1.0012x over previous
; #define LAS __attribute__((address_space(3)))
; __device__ __forceinline__ unsigned pk2(float lo, float hi) { f32x2_t v = {lo, hi}; bf16x2_t b = __builtin_convertvector(v, bf16x2_t); return __builtin_bit_cast(unsigned, b); }
; __device__ __forceinline__ float fexp2(float x) { return __builtin_amdgcn_exp2f(x); }
; __device__ __forceinline__ void sm_update(f32x16& p0, f32x16& p1, float& mref, f32x16& negm, float& l, f32x16 (&o)[2], bool first, LAS float* wsf, int r32, int hi) {
;     ...
;     float s = 0.f;
; #pragma unroll
;     for (int r = 0; r < 16; ++r) { p0[r] = fexp2(p0[r]); p1[r] = fexp2(p1[r]); s += p0[r] + p1[r]; }
;     l += s;
; }
; __device__ __forceinline__ s16x4 vtr(const ldsp p) { typedef short v4i16_t __attribute__((ext_vector_type(4))); return __builtin_bit_cast(s16x4, __builtin_amdgcn_ds_read_tr16_b64_v4i16((LAS v4i16_t*)p)); }
; __device__ __forceinline__ void pv_tile(f32x16 (&o)[2], const ldsp Vt, const f32x16& p0, const f32x16& p1, int lane, int hi) {
;     u32x4 pw[4];
;     pw[0] = (u32x4){pk2(p0[0], p0[1]), pk2(p0[2], p0[3]), pk2(p0[4], p0[5]), pk2(p0[6], p0[7])};
;     pw[1] = (u32x4){pk2(p0[8], p0[9]), pk2(p0[10], p0[11]), pk2(p0[12], p0[13]), pk2(p0[14], p0[15])};
;     pw[2] = (u32x4){pk2(p1[0], p1[1]), pk2(p1[2], p1[3]), pk2(p1[4], p1[5]), pk2(p1[6], p1[7])};
;     pw[3] = (u32x4){pk2(p1[8], p1[9]), pk2(p1[10], p1[11]), pk2(p1[12], p1[13]), pk2(p1[14], p1[15])};
;     const ldsp vp = Vt + ((lane >> 4) & 1) * 32 + (lane & 3) * 8 + (4 * hi + ((lane & 15) >> 2)) * 64;
; #pragma unroll
;     for (int d0 = 0; d0 < 2; ++d0)
; #pragma unroll
;         for (int ks = 0; ks < 4; ++ks) {
;             const s16x4 lo = vtr(vp + d0 * 4096 + ks * 1024), hh = vtr(vp + d0 * 4096 + ks * 1024 + 512);
;             const bf16x8 vf = (bf16x8){lo[0], lo[1], lo[2], lo[3], hh[0], hh[1], hh[2], hh[3]};
;             o[d0] = __builtin_amdgcn_mfma_f32_32x32x16_bf16(__builtin_bit_cast(bf16x8, pw[ks]), vf, o[d0], 0, 0, 0);
;         }
.LBB0_1061:
	v_add3_u32 v107, s33, v247, v248
	v_add3_u32 v107, v107, v249, v250
	ds_read_b64_tr_b16 v[108:109], v107 offset:8192
	ds_read_b64_tr_b16 v[110:111], v107 offset:8704
	ds_read_b64_tr_b16 v[112:113], v107 offset:9216
	ds_read_b64_tr_b16 v[114:115], v107 offset:9728
	ds_read_b64_tr_b16 v[116:117], v107 offset:10240
	ds_read_b64_tr_b16 v[118:119], v107 offset:10752
	ds_read_b64_tr_b16 v[120:121], v107 offset:11264
	ds_read_b64_tr_b16 v[122:123], v107 offset:11776
	ds_read_b64_tr_b16 v[124:125], v107 offset:12288
	ds_read_b64_tr_b16 v[126:127], v107 offset:12800
	v_exp_f32_e32 v104, v64
	v_exp_f32_e32 v105, v80
	v_exp_f32_e32 v176, v65
	v_exp_f32_e32 v96, v81
	v_exp_f32_e32 v106, v82
	v_add_f32_e32 v97, v105, v104
	v_exp_f32_e32 v80, v83
	v_pk_add_f32 v[64:65], v[96:97], v[176:177]
	v_exp_f32_e32 v97, v66
	v_add_f32_e32 v65, v64, v65
	v_exp_f32_e32 v64, v67
	v_exp_f32_e32 v82, v85
	v_add_f32_e32 v81, v106, v97
	v_exp_f32_e32 v98, v87
	v_pk_add_f32 v[66:67], v[80:81], v[64:65]
	v_exp_f32_e32 v65, v68
	v_add_f32_e32 v67, v66, v67
	v_exp_f32_e32 v81, v84
	v_exp_f32_e32 v66, v69
	v_exp_f32_e32 v72, v72
	v_exp_f32_e32 v100, v89
	v_add_f32_e32 v83, v81, v65
	v_pk_add_f32 v[68:69], v[82:83], v[66:67]
	v_exp_f32_e32 v67, v70
	v_add_f32_e32 v85, v68, v69
	v_exp_f32_e32 v83, v86
	v_exp_f32_e32 v84, v71
	v_exp_f32_e32 v102, v91
	v_cvt_pk_bf16_f32 v70, v65, v66
	v_add_f32_e32 v99, v83, v67
	v_pk_add_f32 v[68:69], v[98:99], v[84:85]
	v_exp_f32_e32 v85, v88
	v_add_f32_e32 v87, v68, v69
	v_exp_f32_e32 v86, v73
	v_exp_f32_e32 v73, v74
	v_add_f32_e32 v101, v85, v72
	v_exp_f32_e32 v99, v92
	v_pk_add_f32 v[68:69], v[100:101], v[86:87]
	v_exp_f32_e32 v87, v90
	v_add_f32_e32 v89, v68, v69
	v_exp_f32_e32 v88, v75
	v_exp_f32_e32 v90, v93
	v_add_f32_e32 v103, v87, v73
	v_exp_f32_e32 v92, v95
	v_pk_add_f32 v[68:69], v[102:103], v[88:89]
	v_exp_f32_e32 v89, v76
	v_add_f32_e32 v75, v68, v69
	v_exp_f32_e32 v74, v77
	v_cvt_pk_bf16_f32 v71, v67, v84
	v_add_f32_e32 v91, v99, v89
	v_cvt_pk_bf16_f32 v72, v72, v86
	v_pk_add_f32 v[68:69], v[90:91], v[74:75]
	v_exp_f32_e32 v75, v78
	v_add_f32_e32 v77, v68, v69
	v_exp_f32_e32 v91, v94
	v_exp_f32_e32 v76, v79
	v_cvt_pk_bf16_f32 v78, v81, v82
	v_cvt_pk_bf16_f32 v79, v83, v98
	v_add_f32_e32 v93, v91, v75
	v_pk_add_f32 v[68:69], v[92:93], v[76:77]
	v_cvt_pk_bf16_f32 v77, v106, v80
	v_add_f32_e32 v68, v68, v69
	v_add_f32_e32 v181, v181, v68
	v_cvt_pk_bf16_f32 v68, v104, v176
	v_cvt_pk_bf16_f32 v69, v97, v64
	ds_read_b64_tr_b16 v[80:81], v107 offset:13312
	ds_read_b64_tr_b16 v[82:83], v107 offset:13824
	s_waitcnt lgkmcnt(10)
	v_mfma_f32_32x32x16_bf16 v[32:47], v[68:71], v[108:111], v[32:47]
	v_cvt_pk_bf16_f32 v73, v73, v88
	v_cvt_pk_bf16_f32 v74, v89, v74
	v_cvt_pk_bf16_f32 v75, v75, v76
	ds_read_b64_tr_b16 v[108:109], v107 offset:14336
	ds_read_b64_tr_b16 v[110:111], v107 offset:14848
	v_cvt_pk_bf16_f32 v76, v105, v96
	v_cvt_pk_bf16_f32 v64, v85, v100
	v_cvt_pk_bf16_f32 v65, v87, v102
	s_waitcnt lgkmcnt(10)
	v_mfma_f32_32x32x16_bf16 v[32:47], v[72:75], v[112:115], v[32:47]
	ds_read_b64_tr_b16 v[112:113], v107 offset:15360
	ds_read_b64_tr_b16 v[114:115], v107 offset:15872
	v_cvt_pk_bf16_f32 v66, v99, v90
	v_cvt_pk_bf16_f32 v67, v91, v92
	s_mov_b64 s[88:89], -1
	s_waitcnt lgkmcnt(10)
	v_mfma_f32_32x32x16_bf16 v[32:47], v[76:79], v[116:119], v[32:47]
	s_waitcnt lgkmcnt(8)
	v_mfma_f32_32x32x16_bf16 v[32:47], v[64:67], v[120:123], v[32:47]
	s_waitcnt lgkmcnt(6)
	v_mfma_f32_32x32x16_bf16 v[16:31], v[68:71], v[124:127], v[16:31]
	s_waitcnt lgkmcnt(4)
	v_mfma_f32_32x32x16_bf16 v[16:31], v[72:75], v[80:83], v[16:31]
	s_waitcnt lgkmcnt(2)
	v_mfma_f32_32x32x16_bf16 v[16:31], v[76:79], v[108:111], v[16:31]
	s_waitcnt lgkmcnt(0)
	v_mfma_f32_32x32x16_bf16 v[16:31], v[64:67], v[112:115], v[16:31]
